# RWKV prep: v2t fragments resident per tile; previous-token loads only for the first 16-row block (later blocks: neighbour lane via DPP + carry registers)
# speedup vs baseline: 1.0147x; 1.0036x over previous
; #define LAS __attribute__((address_space(3)))
; __device__ __forceinline__ void st_bf4(bf16_t* p, f32x4 v) { u32x2 w; w.x = cvt_pk_bf16(v[0], v[1]); w.y = cvt_pk_bf16(v[2], v[3]); *(u32x2*)p = w; }
; __device__ __forceinline__ void rwkv_prep_tile(LAS unsigned char* lds, const PrepArgs& P, int tt, int tid) {
;     ...
;     const int h = wave, cb = 64 * h; const int b_ = t0 >> 12, p = b_ * 8 + h;
; #pragma unroll 1
;     for (int m = 0; m < 4; ++m) {
;         const int i = 16 * m + fr; const bf16_t* Ut = P.U + (size_t)(t0 + i) * 1792; const bool hp = (s0 + i) > 0;
;         int fq4 = 4 * fq; asm volatile("" : "+v"(fq4));
;         u32x2 uk[4], pk[4], ur[4], pr[4], uv[4], pv[4]; f32x4 vf[4];
;         { const bf16_t* Up = hp ? Ut - 1792 : Ut; const unsigned pm = hp ? 0xffffffffu : 0u;
; #pragma unroll
;           for (int n = 0; n < 4; ++n) { const int c = cb + 16 * n + fq4;
;               uk[n] = *(const u32x2*)(Ut + 512 + c); ur[n] = *(const u32x2*)(Ut + c); uv[n] = *(const u32x2*)(Ut + 1024 + c);
;               pk[n] = *(const u32x2*)(Up + 512 + c); pr[n] = *(const u32x2*)(Up + c); pv[n] = *(const u32x2*)(Up + 1024 + c);
;               if (P.layer > 0) vf[n] = *(const f32x4*)(P.vfirst + (size_t)(t0 + i) * 512 + c); }
; #pragma unroll
;           for (int n = 0; n < 4; ++n) { pk[n].x &= pm; pk[n].y &= pm; pr[n].x &= pm; pr[n].y &= pm; pv[n].x &= pm; pv[n].y &= pm; } }
;         f32x4 aa[4], acc[4];
;         row_gemm<64>(aa, LAa + i * SW, P.a2t + (size_t)cb * 64, fr, fq);
;         row_gemm<64>(acc, LAw + i * SW, P.w2t + (size_t)cb * 64, fr, fq);
; #pragma unroll
;         for (int n = 0; n < 4; ++n) { const f32x4 a0v = *(LAS const f32x4*)(PRM + 1536 + cb + 16 * n + fq4), w0v = *(LAS const f32x4*)(PRM + 2048 + cb + 16 * n + fq4); f32x4 d;
; #pragma unroll
;             for (int j = 0; j < 4; ++j) { aa[n][j] = sigmoidf_(aa[n][j] + a0v[j]); d[j] = __expf(-0.6065306597f * sigmoidf_(acc[n][j] + w0v[j])); }
;             *(f32x4*)(P.Wd + ((size_t)p * SEQ + s0 + i) * 64 + 4 * fq4 + 4 * n) = d; }
;         row_gemm<128>(acc, LAg + i * SG, P.g2t + (size_t)cb * 128, fr, fq);
; #pragma unroll
;         for (int n = 0; n < 4; ++n) st_bf4(P.Go + (size_t)(t0 + i) * 512 + cb + 16 * n + fq4, acc[n]);
;         if (P.layer > 0) row_gemm<32>(acc, LAvv + i * SVV, P.v2t + (size_t)cb * 32, fr, fq);
.LBB0_415:
	s_add_u32 s16, s28, 0x5b00000
	s_addc_u32 s17, s29, 0
	s_ashr_i32 s6, s21, 3
	s_ashr_i32 s22, s20, 6
	s_and_b32 s18, s20, 0xffffffc0
	s_and_b32 s6, s6, -8
	s_add_i32 s6, s6, s22
	s_lshl_b32 s7, s18, 2
	s_ashr_i32 s19, s18, 31
	s_add_i32 s34, s7, 0
	s_ashr_i32 s7, s6, 31
	s_lshl_b64 s[24:25], s[18:19], 6
	s_add_i32 s31, s34, 0x1bc00
	s_add_i32 s34, s34, 0x1c400
	s_lshl_b64 s[8:9], s[6:7], 12
	s_lshl_b64 s[52:53], s[18:19], 8
	s_ashr_i32 s23, s22, 31
	s_or_b32 s38, s18, 16
	s_or_b32 s39, s18, 32
	s_or_b32 s44, s18, 48
	s_lshl_b64 s[20:21], s[18:19], 1
	s_add_u32 s20, s28, s20
	s_addc_u32 s21, s29, s21
	s_add_u32 s20, s20, 0x7f00000
	s_addc_u32 s21, s21, 0
	s_lshl_b64 s[22:23], s[22:23], 2
	s_add_u32 s22, s28, s22
	s_addc_u32 s23, s29, s23
	s_add_u32 s22, s22, 0x8f00000
	s_addc_u32 s23, s23, 0
	s_lshl_b64 s[54:55], s[18:19], 7
	s_add_u32 s54, s28, s54
	v_lshlrev_b64 v[2:3], 1, v[2:3]
	s_addc_u32 s55, s29, s55
	v_lshlrev_b32_e32 v209, 2, v8
	v_lshlrev_b32_e32 v4, 7, v106
	v_cmp_eq_u32_e64 s[6:7], 0, v8
	v_lshl_add_u64 v[8:9], s[54:55], 0, v[2:3]
	s_mov_b64 s[54:55], 0x3a10000
	v_lshl_add_u64 v[10:11], v[8:9], 0, s[54:55]
	v_mov_b32_e32 v5, v1
	v_or_b32_e32 v12, 0x1000, v4
	v_mov_b32_e32 v13, v1
	v_or_b32_e32 v14, 0x1800, v4
	v_mov_b32_e32 v15, v1
	s_mov_b64 s[54:55], 0x3a10040
	s_add_u32 s52, s28, s52
	v_lshl_add_u64 v[108:109], v[10:11], 0, v[4:5]
	v_lshl_add_u64 v[110:111], v[10:11], 0, v[12:13]
	v_lshl_add_u64 v[112:113], v[10:11], 0, v[14:15]
	v_lshl_add_u64 v[10:11], v[8:9], 0, s[54:55]
	s_mov_b64 s[54:55], 0x3a00000
	s_addc_u32 s53, s29, s53
	v_lshl_add_u64 v[114:115], v[10:11], 0, v[12:13]
	v_lshl_add_u64 v[116:117], v[10:11], 0, v[14:15]
	v_lshl_add_u64 v[10:11], v[8:9], 0, s[54:55]
	s_mov_b64 s[54:55], 0x3a00040
	s_add_u32 s24, s28, s24
	v_lshl_add_u64 v[118:119], v[10:11], 0, v[4:5]
	v_lshl_add_u64 v[4:5], v[8:9], 0, s[54:55]
	s_addc_u32 s25, s29, s25
	v_lshlrev_b32_e32 v0, 6, v106
	v_lshl_add_u64 v[124:125], v[4:5], 0, v[12:13]
	v_lshl_add_u64 v[126:127], v[4:5], 0, v[14:15]
	v_lshl_add_u64 v[4:5], s[52:53], 0, v[2:3]
	v_lshl_add_u64 v[2:3], s[24:25], 0, v[2:3]
	v_lshl_add_u64 v[2:3], v[2:3], 0, v[0:1]
	s_mov_b64 s[24:25], 0x3a48000
	v_lshl_add_u64 v[154:155], v[2:3], 0, s[24:25]
	s_add_i32 s24, 0, 0x19000
	s_mov_b64 s[52:53], 0x3a20000
	v_mov_b32_e32 v0, s24
	s_movk_i32 s24, 0x50
	v_lshlrev_b32_e32 v6, 8, v106
	v_lshl_add_u64 v[8:9], v[4:5], 0, s[52:53]
	v_mov_b32_e32 v7, v1
	v_mad_u32_u24 v0, v106, s24, v0
	v_readlane_b32 s24, v255, 11
	v_lshl_add_u64 v[120:121], v[10:11], 0, v[12:13]
	v_lshl_add_u64 v[122:123], v[10:11], 0, v[14:15]
	v_lshl_add_u64 v[128:129], v[8:9], 0, v[6:7]
	v_or_b32_e32 v10, 0x1000, v6
	v_mov_b32_e32 v11, v1
	v_or_b32_e32 v12, 0x2000, v6
	v_or_b32_e32 v6, 0x3000, v6
	s_mov_b64 s[52:53], 0x3a20040
	v_mov_b32_e32 v2, s24
	s_movk_i32 s24, 0x110
	v_lshl_add_u64 v[130:131], v[8:9], 0, v[10:11]
	v_lshl_add_u64 v[132:133], v[8:9], 0, v[12:13]
	v_lshl_add_u64 v[134:135], v[8:9], 0, v[6:7]
	v_lshl_add_u64 v[8:9], v[4:5], 0, s[52:53]
	s_mov_b64 s[52:53], 0x3a20080
	v_mad_u32_u24 v210, v106, s24, v2
	s_and_b32 s24, s27, 7
	v_lshl_add_u64 v[136:137], v[8:9], 0, v[10:11]
	v_lshl_add_u64 v[138:139], v[8:9], 0, v[12:13]
	v_lshl_add_u64 v[140:141], v[8:9], 0, v[6:7]
	v_lshl_add_u64 v[8:9], v[4:5], 0, s[52:53]
	s_mov_b64 s[52:53], 0x3a200c0
	s_lshl_b32 s24, s24, 11
	s_lshl_b32 s25, s30, 6
	s_or_b32 s8, s8, s26
	v_mov_b32_e32 v107, v1
	v_lshl_add_u64 v[4:5], v[4:5], 0, s[52:53]
	s_add_i32 s24, s24, s25
	v_lshl_add_u64 v[2:3], s[8:9], 0, v[106:107]
	v_readlane_b32 s8, v254, 55
	v_lshl_add_u64 v[148:149], v[4:5], 0, v[10:11]
	v_lshl_add_u64 v[150:151], v[4:5], 0, v[12:13]
	v_lshl_add_u64 v[152:153], v[4:5], 0, v[6:7]
	v_or_b32_e32 v211, s24, v106
	s_movk_i32 s24, 0x90
	v_lshlrev_b64 v[4:5], 8, v[2:3]
	v_lshlrev_b64 v[2:3], 9, v[2:3]
	v_readlane_b32 s9, v254, 56
	s_mov_b32 s35, 0
	v_lshl_add_u64 v[142:143], v[8:9], 0, v[10:11]
	v_lshl_add_u64 v[144:145], v[8:9], 0, v[12:13]
	v_lshl_add_u64 v[146:147], v[8:9], 0, v[6:7]
	v_mad_u32_u24 v212, v106, s24, 0
	v_lshl_add_u64 v[156:157], s[92:93], 0, v[4:5]
	v_lshl_add_u64 v[158:159], s[8:9], 0, v[2:3]
	s_waitcnt lgkmcnt(0)
	s_barrier
	global_load_dwordx4 v[18:21], v[128:129], off
	global_load_dwordx4 v[22:25], v[128:129], off offset:64
	global_load_dwordx4 v[26:29], v[128:129], off offset:128
	global_load_dwordx4 v[30:33], v[128:129], off offset:192
	global_load_dwordx4 v[34:37], v[130:131], off
	global_load_dwordx4 v[38:41], v[136:137], off
	global_load_dwordx4 v[42:45], v[142:143], off
	global_load_dwordx4 v[46:49], v[148:149], off
	global_load_dwordx4 v[50:53], v[132:133], off
	global_load_dwordx4 v[54:57], v[138:139], off
	global_load_dwordx4 v[58:61], v[144:145], off
	global_load_dwordx4 v[62:65], v[150:151], off
	global_load_dwordx4 v[66:69], v[134:135], off
	global_load_dwordx4 v[70:73], v[140:141], off
	global_load_dwordx4 v[74:77], v[146:147], off
	global_load_dwordx4 v[78:81], v[152:153], off
	global_load_dwordx4 v[190:193], v[154:155], off
	global_load_dwordx4 v[216:219], v[154:155], off offset:1024
	global_load_dwordx4 v[220:223], v[154:155], off offset:2048
	global_load_dwordx4 v[224:227], v[154:155], off offset:3072
	s_mov_b32 s46, 0
	v_mov_b32_e32 v176, v210
	s_waitcnt vmcnt(0)

; __device__ __forceinline__ void rwkv_prep_tile(LAS unsigned char* lds, const PrepArgs& P, int tt, int tid) {
;     ...
;         const int i = 16 * m + fr; const bf16_t* Ut = P.U + (size_t)(t0 + i) * 1792; const bool hp = (s0 + i) > 0;
;         int fq4 = 4 * fq; asm volatile("" : "+v"(fq4));
;         u32x2 uk[4], pk[4], ur[4], pr[4], uv[4], pv[4]; f32x4 vf[4];
;         { const bf16_t* Up = hp ? Ut - 1792 : Ut; const unsigned pm = hp ? 0xffffffffu : 0u;
; #pragma unroll
;           for (int n = 0; n < 4; ++n) { const int c = cb + 16 * n + fq4;
;               uk[n] = *(const u32x2*)(Ut + 512 + c); ur[n] = *(const u32x2*)(Ut + c); uv[n] = *(const u32x2*)(Ut + 1024 + c);
;               pk[n] = *(const u32x2*)(Up + 512 + c); pr[n] = *(const u32x2*)(Up + c); pv[n] = *(const u32x2*)(Up + 1024 + c);
;               if (P.layer > 0) vf[n] = *(const f32x4*)(P.vfirst + (size_t)(t0 + i) * 512 + c); }
; #pragma unroll
;           for (int n = 0; n < 4; ++n) { pk[n].x &= pm; pk[n].y &= pm; pr[n].x &= pm; pr[n].y &= pm; pv[n].x &= pm; pv[n].y &= pm; } }
.LBB0_417:
	v_add_u32_e32 v20, s35, v106
	v_add_u32_e32 v160, s35, v211
	s_waitcnt lgkmcnt(0)
	v_mov_b64_e32 v[18:19], s[12:13]
	v_mov_b32_e32 v98, v209
	v_mad_i64_i32 v[18:19], s[8:9], v160, s80, v[18:19]
	v_or_b32_e32 v20, s26, v20
	v_cmp_eq_u32_e64 s[8:9], 0, v20
	v_add_u32_e32 v70, s18, v98
	v_ashrrev_i32_e32 v71, 31, v70
	v_cndmask_b32_e64 v21, -1, 0, s[8:9]
	v_cndmask_b32_e64 v20, v242, 0, s[8:9]
	v_lshlrev_b64 v[22:23], 1, v[70:71]
	v_lshl_add_u64 v[20:21], v[18:19], 0, v[20:21]
	v_lshl_add_u64 v[18:19], v[18:19], 0, v[22:23]
	v_lshl_add_u64 v[20:21], v[20:21], 0, v[22:23]
	global_load_dwordx2 v[196:197], v[18:19], off offset:1024
	global_load_dwordx2 v[74:75], v[18:19], off offset:2048
	global_load_dwordx2 v[164:165], v[18:19], off
	v_ashrrev_i32_e32 v161, 31, v160
	v_lshlrev_b64 v[22:23], 11, v[160:161]
	v_lshl_add_u64 v[90:91], s[16:17], 0, v[22:23]
	s_and_b64 vcc, exec, s[4:5]
	v_lshl_add_u64 v[82:83], v[70:71], 2, v[90:91]
	s_cbranch_vccnz .LBB0_419
	global_load_dwordx4 v[14:17], v[82:83], off
.LBB0_419:
	global_load_dwordx2 v[184:185], v[18:19], off offset:1056
	global_load_dwordx2 v[86:87], v[18:19], off offset:2080
	global_load_dwordx2 v[168:169], v[18:19], off offset:32
	s_and_b64 vcc, exec, s[4:5]
	s_cbranch_vccnz .LBB0_421
	global_load_dwordx4 v[10:13], v[82:83], off offset:64
.LBB0_421:
	global_load_dwordx2 v[178:179], v[18:19], off offset:1088
	global_load_dwordx2 v[104:105], v[18:19], off offset:2112
	global_load_dwordx2 v[176:177], v[18:19], off offset:64
	s_and_b64 vcc, exec, s[4:5]
	s_cbranch_vccnz .LBB0_423
	global_load_dwordx4 v[6:9], v[82:83], off offset:128
.LBB0_423:
	global_load_dwordx2 v[174:175], v[18:19], off offset:1120
	global_load_dwordx2 v[102:103], v[18:19], off offset:2144
	global_load_dwordx2 v[172:173], v[18:19], off offset:96
	s_and_b64 vcc, exec, s[4:5]
	s_cbranch_vccnz .LBB0_425
	global_load_dwordx4 v[2:5], v[82:83], off offset:192
.LBB0_425:
	s_cmp_lg_u32 s35, 0
	s_cbranch_scc1 .Lp4_skip_p
	global_load_dwordx2 v[166:167], v[20:21], off
	global_load_dwordx2 v[200:201], v[20:21], off offset:1024
	global_load_dwordx2 v[72:73], v[20:21], off offset:2048
	global_load_dwordx2 v[170:171], v[20:21], off offset:32
	global_load_dwordx2 v[202:203], v[20:21], off offset:1056
	global_load_dwordx2 v[84:85], v[20:21], off offset:2080
	global_load_dwordx2 v[194:195], v[20:21], off offset:64
	global_load_dwordx2 v[198:199], v[20:21], off offset:1088
	global_load_dwordx2 v[92:93], v[20:21], off offset:2112
	global_load_dwordx2 v[180:181], v[20:21], off offset:96
	global_load_dwordx2 v[182:183], v[20:21], off offset:1120
	global_load_dwordx2 v[100:101], v[20:21], off offset:2144
.Lp4_skip_p:
	global_load_dwordx4 v[18:21], v[108:109], off
	global_load_dwordx4 v[22:25], v[108:109], off offset:2048
	global_load_dwordx4 v[26:29], v[110:111], off
	v_add_u32_e32 v62, v212, v208
	ds_read_b128 v[34:37], v62 offset:9216
	ds_read_b128 v[30:33], v62 offset:9280
	global_load_dwordx4 v[38:41], v[108:109], off offset:64
	global_load_dwordx4 v[42:45], v[112:113], off
	global_load_dwordx4 v[46:49], v[108:109], off offset:2112
	global_load_dwordx4 v[50:53], v[118:119], off
	global_load_dwordx4 v[58:61], v[118:119], off offset:64
	v_lshlrev_b32_e32 v162, 2, v98
	v_add_u32_e32 v71, s34, v162
	v_lshl_add_u64 v[88:89], v[156:157], 0, s[10:11]
	v_ashrrev_i32_e32 v163, 31, v162
	s_mov_b32 s24, 0xe100000
	v_ashrrev_i32_e32 v99, 31, v98
	s_waitcnt vmcnt(7) lgkmcnt(1)
	v_mfma_f32_16x16x32_bf16 v[18:21], v[18:21], v[34:37], 0
	s_waitcnt vmcnt(5)
	v_mfma_f32_16x16x32_bf16 v[54:57], v[26:29], v[34:37], 0
	global_load_dwordx4 v[26:29], v[118:119], off offset:2048
	v_mfma_f32_16x16x32_bf16 v[22:25], v[22:25], v[34:37], 0
	s_waitcnt vmcnt(4)
	v_mfma_f32_16x16x32_bf16 v[34:37], v[42:45], v[34:37], 0
	ds_read_b128 v[42:45], v62
	ds_read_b128 v[62:65], v62 offset:64
	global_load_dwordx4 v[66:69], v[120:121], off
	global_load_dwordx4 v[76:79], v[118:119], off offset:2112
	s_waitcnt vmcnt(4) lgkmcnt(1)
	v_mfma_f32_16x16x32_bf16 v[50:53], v[50:53], v[42:45], 0
	v_mfma_f32_16x16x32_bf16 v[22:25], v[46:49], v[30:33], v[22:25]
	s_waitcnt vmcnt(3) lgkmcnt(0)
	v_mfma_f32_16x16x32_bf16 v[50:53], v[58:61], v[62:65], v[50:53]
	v_lshl_add_u64 v[58:59], v[162:163], 2, v[88:89]
	v_add_co_u32_e32 v58, vcc, s24, v58
	s_waitcnt vmcnt(1)
	v_mfma_f32_16x16x32_bf16 v[66:69], v[66:69], v[42:45], 0
	v_addc_co_u32_e32 v59, vcc, 0, v59, vcc
	s_and_b64 vcc, exec, s[4:5]
	v_mfma_f32_16x16x32_bf16 v[94:97], v[26:29], v[42:45], 0
	global_load_dwordx4 v[26:29], v[122:123], off
	s_waitcnt vmcnt(1)
	v_mfma_f32_16x16x32_bf16 v[76:79], v[76:79], v[62:65], v[94:97]
	s_waitcnt vmcnt(0)
	s_cmp_eq_u32 s35, 0
	s_cbranch_scc1 .Lp4_carry
; __device__ __forceinline__ void rwkv_prep_tile(LAS unsigned char* lds, const PrepArgs& P, int tt, int tid) {
;     ...
;         { const bf16_t* Up = hp ? Ut - 1792 : Ut; const unsigned pm = hp ? 0xffffffffu : 0u;
; #pragma unroll
;           for (int n = 0; n < 4; ++n) { const int c = cb + 16 * n + fq4;
;               uk[n] = *(const u32x2*)(Ut + 512 + c); ur[n] = *(const u32x2*)(Ut + c); uv[n] = *(const u32x2*)(Ut + 1024 + c);
;               pk[n] = *(const u32x2*)(Up + 512 + c); pr[n] = *(const u32x2*)(Up + c); pv[n] = *(const u32x2*)(Up + 1024 + c);
;               if (P.layer > 0) vf[n] = *(const f32x4*)(P.vfirst + (size_t)(t0 + i) * 512 + c); }
; #pragma unroll
;           for (int n = 0; n < 4; ++n) { pk[n].x &= pm; pk[n].y &= pm; pr[n].x &= pm; pr[n].y &= pm; pv[n].x &= pm; pv[n].y &= pm; } }
	v_mov_b32_dpp v166, v128 row_ror:1 row_mask:0xf bank_mask:0x1
	v_mov_b32_dpp v167, v129 row_ror:1 row_mask:0xf bank_mask:0x1
	v_mov_b32_dpp v170, v130 row_ror:1 row_mask:0xf bank_mask:0x1
	v_mov_b32_dpp v171, v131 row_ror:1 row_mask:0xf bank_mask:0x1
	v_mov_b32_dpp v194, v132 row_ror:1 row_mask:0xf bank_mask:0x1
	v_mov_b32_dpp v195, v133 row_ror:1 row_mask:0xf bank_mask:0x1
	v_mov_b32_dpp v180, v134 row_ror:1 row_mask:0xf bank_mask:0x1
	v_mov_b32_dpp v181, v135 row_ror:1 row_mask:0xf bank_mask:0x1
	v_mov_b32_dpp v200, v136 row_ror:1 row_mask:0xf bank_mask:0x1
	v_mov_b32_dpp v201, v137 row_ror:1 row_mask:0xf bank_mask:0x1
	v_mov_b32_dpp v202, v138 row_ror:1 row_mask:0xf bank_mask:0x1
	v_mov_b32_dpp v203, v139 row_ror:1 row_mask:0xf bank_mask:0x1
	v_mov_b32_dpp v198, v140 row_ror:1 row_mask:0xf bank_mask:0x1
	v_mov_b32_dpp v199, v141 row_ror:1 row_mask:0xf bank_mask:0x1
	v_mov_b32_dpp v182, v142 row_ror:1 row_mask:0xf bank_mask:0x1
	v_mov_b32_dpp v183, v143 row_ror:1 row_mask:0xf bank_mask:0x1
	v_mov_b32_dpp v72, v144 row_ror:1 row_mask:0xf bank_mask:0x1
	v_mov_b32_dpp v73, v145 row_ror:1 row_mask:0xf bank_mask:0x1
	v_mov_b32_dpp v84, v146 row_ror:1 row_mask:0xf bank_mask:0x1
	v_mov_b32_dpp v85, v147 row_ror:1 row_mask:0xf bank_mask:0x1
	v_mov_b32_dpp v92, v148 row_ror:1 row_mask:0xf bank_mask:0x1
	v_mov_b32_dpp v93, v149 row_ror:1 row_mask:0xf bank_mask:0x1
	v_mov_b32_dpp v100, v150 row_ror:1 row_mask:0xf bank_mask:0x1
	v_mov_b32_dpp v101, v151 row_ror:1 row_mask:0xf bank_mask:0x1
	v_mov_b32_dpp v166, v164 row_shr:1 row_mask:0xf bank_mask:0xf
	v_mov_b32_dpp v167, v165 row_shr:1 row_mask:0xf bank_mask:0xf
	v_mov_b32_dpp v170, v168 row_shr:1 row_mask:0xf bank_mask:0xf
	v_mov_b32_dpp v171, v169 row_shr:1 row_mask:0xf bank_mask:0xf
	v_mov_b32_dpp v194, v176 row_shr:1 row_mask:0xf bank_mask:0xf
	v_mov_b32_dpp v195, v177 row_shr:1 row_mask:0xf bank_mask:0xf
	v_mov_b32_dpp v180, v172 row_shr:1 row_mask:0xf bank_mask:0xf
	v_mov_b32_dpp v181, v173 row_shr:1 row_mask:0xf bank_mask:0xf
	v_mov_b32_dpp v200, v196 row_shr:1 row_mask:0xf bank_mask:0xf
	v_mov_b32_dpp v201, v197 row_shr:1 row_mask:0xf bank_mask:0xf
	v_mov_b32_dpp v202, v184 row_shr:1 row_mask:0xf bank_mask:0xf
	v_mov_b32_dpp v203, v185 row_shr:1 row_mask:0xf bank_mask:0xf
	v_mov_b32_dpp v198, v178 row_shr:1 row_mask:0xf bank_mask:0xf
	v_mov_b32_dpp v199, v179 row_shr:1 row_mask:0xf bank_mask:0xf
	v_mov_b32_dpp v182, v174 row_shr:1 row_mask:0xf bank_mask:0xf
	v_mov_b32_dpp v183, v175 row_shr:1 row_mask:0xf bank_mask:0xf
	v_mov_b32_dpp v72, v74 row_shr:1 row_mask:0xf bank_mask:0xf
	v_mov_b32_dpp v73, v75 row_shr:1 row_mask:0xf bank_mask:0xf
	v_mov_b32_dpp v84, v86 row_shr:1 row_mask:0xf bank_mask:0xf
	v_mov_b32_dpp v85, v87 row_shr:1 row_mask:0xf bank_mask:0xf
	v_mov_b32_dpp v92, v104 row_shr:1 row_mask:0xf bank_mask:0xf
	v_mov_b32_dpp v93, v105 row_shr:1 row_mask:0xf bank_mask:0xf
	v_mov_b32_dpp v100, v102 row_shr:1 row_mask:0xf bank_mask:0xf
	v_mov_b32_dpp v101, v103 row_shr:1 row_mask:0xf bank_mask:0xf
; #define LAS __attribute__((address_space(3)))
; __device__ __forceinline__ void st_bf4(bf16_t* p, f32x4 v) { u32x2 w; w.x = cvt_pk_bf16(v[0], v[1]); w.y = cvt_pk_bf16(v[2], v[3]); *(u32x2*)p = w; }
; __device__ __forceinline__ float sigmoidf_(float x) { return __builtin_amdgcn_rcpf(1.0f + __expf(-x)); }
; __device__ __forceinline__ void rwkv_prep_tile(LAS unsigned char* lds, const PrepArgs& P, int tt, int tid) {
;     ...
;         { const bf16_t* Up = hp ? Ut - 1792 : Ut; const unsigned pm = hp ? 0xffffffffu : 0u;
; #pragma unroll
;           for (int n = 0; n < 4; ++n) { const int c = cb + 16 * n + fq4;
;               uk[n] = *(const u32x2*)(Ut + 512 + c); ur[n] = *(const u32x2*)(Ut + c); uv[n] = *(const u32x2*)(Ut + 1024 + c);
;               pk[n] = *(const u32x2*)(Up + 512 + c); pr[n] = *(const u32x2*)(Up + c); pv[n] = *(const u32x2*)(Up + 1024 + c);
;               if (P.layer > 0) vf[n] = *(const f32x4*)(P.vfirst + (size_t)(t0 + i) * 512 + c); }
; #pragma unroll
;           for (int n = 0; n < 4; ++n) { pk[n].x &= pm; pk[n].y &= pm; pr[n].x &= pm; pr[n].y &= pm; pv[n].x &= pm; pv[n].y &= pm; } }
;     ...
;         row_gemm<64>(aa, LAa + i * SW, P.a2t + (size_t)cb * 64, fr, fq);
;         row_gemm<64>(acc, LAw + i * SW, P.w2t + (size_t)cb * 64, fr, fq);
; #pragma unroll
;         for (int n = 0; n < 4; ++n) { const f32x4 a0v = *(LAS const f32x4*)(PRM + 1536 + cb + 16 * n + fq4), w0v = *(LAS const f32x4*)(PRM + 2048 + cb + 16 * n + fq4); f32x4 d;
; #pragma unroll
;             for (int j = 0; j < 4; ++j) { aa[n][j] = sigmoidf_(aa[n][j] + a0v[j]); d[j] = __expf(-0.6065306597f * sigmoidf_(acc[n][j] + w0v[j])); }
;             *(f32x4*)(P.Wd + ((size_t)p * SEQ + s0 + i) * 64 + 4 * fq4 + 4 * n) = d; }
;         row_gemm<128>(acc, LAg + i * SG, P.g2t + (size_t)cb * 128, fr, fq);
; #pragma unroll
;         for (int n = 0; n < 4; ++n) st_bf4(P.Go + (size_t)(t0 + i) * 512 + cb + 16 * n + fq4, acc[n]);
;         if (P.layer > 0) row_gemm<32>(acc, LAvv + i * SVV, P.v2t + (size_t)cb * 32, fr, fq);
.Lp4_carry:
	v_mov_b32_e32 v128, v164
	v_mov_b32_e32 v129, v165
	v_mov_b32_e32 v130, v168
	v_mov_b32_e32 v131, v169
	v_mov_b32_e32 v132, v176
	v_mov_b32_e32 v133, v177
	v_mov_b32_e32 v134, v172
	v_mov_b32_e32 v135, v173
	v_mov_b32_e32 v136, v196
	v_mov_b32_e32 v137, v197
	v_mov_b32_e32 v138, v184
	v_mov_b32_e32 v139, v185
	v_mov_b32_e32 v140, v178
	v_mov_b32_e32 v141, v179
	v_mov_b32_e32 v142, v174
	v_mov_b32_e32 v143, v175
	v_mov_b32_e32 v144, v74
	v_mov_b32_e32 v145, v75
	v_mov_b32_e32 v146, v86
	v_mov_b32_e32 v147, v87
	v_mov_b32_e32 v148, v104
	v_mov_b32_e32 v149, v105
	v_mov_b32_e32 v150, v102
	v_mov_b32_e32 v151, v103
	v_mfma_f32_16x16x32_bf16 v[42:45], v[26:29], v[42:45], 0
	v_mfma_f32_16x16x32_bf16 v[26:29], v[38:41], v[30:33], v[18:21]
	s_nop 2
	global_load_dwordx4 v[18:21], v[114:115], off
	global_load_dwordx4 v[46:49], v[124:125], off
	global_load_dwordx4 v[38:41], v[116:117], off
	s_waitcnt vmcnt(1)
	v_mfma_f32_16x16x32_bf16 v[46:49], v[46:49], v[62:65], v[66:69]
	v_mfma_f32_16x16x32_bf16 v[18:21], v[18:21], v[30:33], v[54:57]
	s_nop 2
	global_load_dwordx4 v[54:57], v[126:127], off
	ds_read_b128 v[94:97], v71
	ds_read_b128 v[204:207], v71 offset:64
	s_waitcnt vmcnt(1)
	v_mfma_f32_16x16x32_bf16 v[30:33], v[38:41], v[30:33], v[34:37]
	s_waitcnt lgkmcnt(1)
	v_add_f32_e32 v50, v50, v94
	v_add_f32_e32 v51, v51, v95
	v_add_f32_e32 v52, v52, v96
	v_add_f32_e32 v53, v53, v97
	v_mul_f32_e32 v50, 0xbfb8aa3b, v50
	v_mul_f32_e32 v51, 0xbfb8aa3b, v51
	v_mul_f32_e32 v52, 0xbfb8aa3b, v52
	v_mul_f32_e32 v53, 0xbfb8aa3b, v53
	v_exp_f32_e32 v50, v50
	v_exp_f32_e32 v51, v51
	v_exp_f32_e32 v52, v52
	v_exp_f32_e32 v53, v53
	v_add_f32_e32 v50, 1.0, v50
	v_add_f32_e32 v51, 1.0, v51
	v_add_f32_e32 v52, 1.0, v52
	v_add_f32_e32 v53, 1.0, v53
	v_rcp_f32_e32 v50, v50
	v_rcp_f32_e32 v51, v51
	v_rcp_f32_e32 v52, v52
	v_rcp_f32_e32 v53, v53
	v_mul_f32_e32 v50, 0xbf1b4598, v50
	v_mul_f32_e32 v51, 0xbf1b4598, v51
	v_mul_f32_e32 v52, 0xbf1b4598, v52
	v_mul_f32_e32 v53, 0xbf1b4598, v53
	v_mul_f32_e32 v50, 0x3fb8aa3b, v50
	v_mul_f32_e32 v51, 0x3fb8aa3b, v51
	v_mul_f32_e32 v52, 0x3fb8aa3b, v52
	v_mul_f32_e32 v53, 0x3fb8aa3b, v53
	v_exp_f32_e32 v50, v50
	v_exp_f32_e32 v51, v51
	v_exp_f32_e32 v52, v52
	v_exp_f32_e32 v53, v53
	s_waitcnt vmcnt(0)
	v_mfma_f32_16x16x32_bf16 v[42:45], v[54:57], v[62:65], v[42:45]
	ds_read_b128 v[60:63], v71 offset:128
	ds_read_b128 v[64:67], v71 offset:192
	s_waitcnt lgkmcnt(2)
	v_add_f32_e32 v54, v76, v204
	v_add_f32_e32 v55, v77, v205
	v_add_f32_e32 v56, v78, v206
	v_add_f32_e32 v57, v79, v207
	v_mul_f32_e32 v54, 0xbfb8aa3b, v54
	v_mul_f32_e32 v55, 0xbfb8aa3b, v55
	v_mul_f32_e32 v56, 0xbfb8aa3b, v56
	v_mul_f32_e32 v57, 0xbfb8aa3b, v57
	s_waitcnt lgkmcnt(1)
	v_add_f32_e32 v46, v46, v60
	v_add_f32_e32 v47, v47, v61
	v_add_f32_e32 v48, v48, v62
	v_add_f32_e32 v49, v49, v63
	v_exp_f32_e32 v54, v54
	v_exp_f32_e32 v55, v55
	v_exp_f32_e32 v56, v56
	v_exp_f32_e32 v57, v57
	v_mul_f32_e32 v46, 0xbfb8aa3b, v46
	v_mul_f32_e32 v47, 0xbfb8aa3b, v47
	v_mul_f32_e32 v48, 0xbfb8aa3b, v48
	v_mul_f32_e32 v49, 0xbfb8aa3b, v49
	s_waitcnt lgkmcnt(0)
	v_add_f32_e32 v42, v42, v64
	v_add_f32_e32 v43, v43, v65
	v_add_f32_e32 v44, v44, v66
	v_add_f32_e32 v45, v45, v67
	v_exp_f32_e32 v46, v46
	v_exp_f32_e32 v47, v47
	v_exp_f32_e32 v48, v48
	v_exp_f32_e32 v49, v49
	v_mul_f32_e32 v42, 0xbfb8aa3b, v42
	v_mul_f32_e32 v43, 0xbfb8aa3b, v43
	v_mul_f32_e32 v44, 0xbfb8aa3b, v44
	v_mul_f32_e32 v45, 0xbfb8aa3b, v45
	v_exp_f32_e32 v42, v42
	v_exp_f32_e32 v43, v43
	v_exp_f32_e32 v44, v44
	v_exp_f32_e32 v45, v45
	v_add_f32_e32 v54, 1.0, v54
	v_add_f32_e32 v55, 1.0, v55
	v_add_f32_e32 v56, 1.0, v56
	v_add_f32_e32 v57, 1.0, v57
	v_rcp_f32_e32 v54, v54
	v_rcp_f32_e32 v55, v55
	v_rcp_f32_e32 v56, v56
	v_rcp_f32_e32 v57, v57
	v_add_f32_e32 v46, 1.0, v46
	v_add_f32_e32 v47, 1.0, v47
	v_add_f32_e32 v48, 1.0, v48
	v_add_f32_e32 v49, 1.0, v49
	v_rcp_f32_e32 v46, v46
	v_rcp_f32_e32 v47, v47
	v_rcp_f32_e32 v48, v48
	v_rcp_f32_e32 v49, v49
	v_add_f32_e32 v42, 1.0, v42
	v_add_f32_e32 v43, 1.0, v43
	v_add_f32_e32 v44, 1.0, v44
	v_add_f32_e32 v45, 1.0, v45
	v_rcp_f32_e32 v42, v42
	v_rcp_f32_e32 v43, v43
	v_rcp_f32_e32 v44, v44
	v_rcp_f32_e32 v45, v45
	v_mul_f32_e32 v54, 0xbf1b4598, v54
	v_mul_f32_e32 v55, 0xbf1b4598, v55
	v_mul_f32_e32 v56, 0xbf1b4598, v56
	v_mul_f32_e32 v57, 0xbf1b4598, v57
	v_mul_f32_e32 v54, 0x3fb8aa3b, v54
	v_mul_f32_e32 v55, 0x3fb8aa3b, v55
	v_mul_f32_e32 v56, 0x3fb8aa3b, v56
	v_mul_f32_e32 v57, 0x3fb8aa3b, v57
	v_mul_f32_e32 v46, 0xbf1b4598, v46
	v_mul_f32_e32 v47, 0xbf1b4598, v47
	v_mul_f32_e32 v48, 0xbf1b4598, v48
	v_mul_f32_e32 v49, 0xbf1b4598, v49
	v_exp_f32_e32 v54, v54
	v_exp_f32_e32 v55, v55
	v_exp_f32_e32 v56, v56
	v_exp_f32_e32 v57, v57
	v_mul_f32_e32 v46, 0x3fb8aa3b, v46
	v_mul_f32_e32 v47, 0x3fb8aa3b, v47
	v_mul_f32_e32 v48, 0x3fb8aa3b, v48
	v_mul_f32_e32 v49, 0x3fb8aa3b, v49
	v_mul_f32_e32 v42, 0xbf1b4598, v42
	v_mul_f32_e32 v43, 0xbf1b4598, v43
	v_mul_f32_e32 v44, 0xbf1b4598, v44
	v_mul_f32_e32 v45, 0xbf1b4598, v45
	v_exp_f32_e32 v46, v46
	v_exp_f32_e32 v47, v47
	v_exp_f32_e32 v48, v48
	v_exp_f32_e32 v49, v49
	v_mul_f32_e32 v42, 0x3fb8aa3b, v42
	v_mul_f32_e32 v43, 0x3fb8aa3b, v43
	v_mul_f32_e32 v44, 0x3fb8aa3b, v44
	v_mul_f32_e32 v45, 0x3fb8aa3b, v45
	v_exp_f32_e32 v42, v42
	v_exp_f32_e32 v43, v43
	v_exp_f32_e32 v44, v44
	v_exp_f32_e32 v45, v45
	global_store_dwordx4 v[58:59], v[50:53], off
	global_store_dwordx4 v[58:59], v[54:57], off offset:16
	global_store_dwordx4 v[58:59], v[46:49], off offset:32
	global_store_dwordx4 v[58:59], v[42:45], off offset:48
	s_nop 1
	v_add_u32_e32 v34, s31, v162
	ds_read_b128 v[46:49], v34
	ds_read_b128 v[42:45], v34 offset:64
	ds_read_b128 v[38:41], v34 offset:128
	ds_read_b128 v[34:37], v34 offset:192
	s_cbranch_vccnz .LBB0_427
	v_add_u32_e32 v58, v0, v208
	ds_read_b128 v[62:65], v58
	s_waitcnt lgkmcnt(0)
	v_mfma_f32_16x16x32_bf16 v[66:69], v[190:193], v[62:65], 0
	v_mfma_f32_16x16x32_bf16 v[58:61], v[216:219], v[62:65], 0
	v_mfma_f32_16x16x32_bf16 v[54:57], v[220:223], v[62:65], 0
	v_mfma_f32_16x16x32_bf16 v[62:65], v[224:227], v[62:65], 0
